# adds: pipelined attention unit prologue fetches the second K/V tile together with the first
# speedup vs baseline: 1.0050x; 1.0050x over previous
.LBB0_586:
	v_mov_b32_e32 v40, v0
	s_add_i32 s18, s80, -1
	v_ashrrev_i32_e32 v178, 6, v40
	v_and_b32_e32 v165, 31, v40
	v_lshlrev_b32_e32 v1, 5, v178
	v_or_b32_e32 v2, v1, v165
	v_add_u32_e32 v179, s82, v2
	v_min_i32_e32 v2, s18, v179
	v_ashrrev_i32_e32 v5, 31, v2
	v_mad_u64_u32 v[2:3], s[18:19], v2, s26, 0
	v_mov_b32_e32 v4, v3
	v_mad_u64_u32 v[4:5], s[18:19], v5, s26, v[4:5]
	v_bfe_u32 v164, v40, 5, 1
	v_mov_b32_e32 v3, v4
	v_lshl_add_u64 v[2:3], v[2:3], 1, s[4:5]
	v_lshlrev_b32_e32 v146, 4, v164
	v_mov_b32_e32 v147, v167
	v_lshl_add_u64 v[2:3], v[2:3], 0, v[146:147]
	global_load_dwordx4 v[142:145], v[2:3], off
	global_load_dwordx4 v[138:141], v[2:3], off offset:32
	global_load_dwordx4 v[134:137], v[2:3], off offset:64
	global_load_dwordx4 v[130:133], v[2:3], off offset:96
	global_load_dwordx4 v[126:129], v[2:3], off offset:128
	global_load_dwordx4 v[122:125], v[2:3], off offset:160
	global_load_dwordx4 v[118:121], v[2:3], off offset:192
	global_load_dwordx4 v[114:117], v[2:3], off offset:224
	v_ashrrev_i32_e32 v2, 4, v40
	v_and_b32_e32 v5, 0xfffff0, v2
	v_lshlrev_b32_e32 v6, 1, v2
	v_and_or_b32 v5, v6, 8, v5
	v_lshrrev_b32_e32 v6, 1, v2
	v_and_b32_e32 v7, 3, v2
	v_and_or_b32 v6, v6, 4, v7
	v_lshlrev_b32_e32 v18, 6, v6
	v_add_u32_e32 v6, 32, v2
	v_and_b32_e32 v7, 0xfffff0, v6
	v_lshlrev_b32_e32 v6, 1, v6
	v_lshlrev_b32_e32 v3, 3, v40
	v_and_or_b32 v6, v6, 8, v7
	v_and_b32_e32 v4, 0x78, v3
	v_lshrrev_b32_e32 v5, 1, v5
	v_bfe_u32 v3, v3, 5, 2
	v_lshrrev_b32_e32 v6, 1, v6
	v_or_b32_e32 v5, v5, v3
	v_or_b32_e32 v3, v6, v3
	v_mul_lo_u32 v2, v2, s26
	v_lshlrev_b32_e32 v19, 9, v3
	v_or_b32_e32 v3, v2, v4
	v_lshl_add_u32 v2, s26, 5, v2
	v_or_b32_e32 v2, v2, v4
	v_ashrrev_i32_e32 v4, 31, v40
	v_lshrrev_b32_e32 v4, 28, v4
	v_add_u32_e32 v4, v40, v4
	s_lshl_b32 s4, s26, 1
	v_ashrrev_i32_e32 v6, 4, v4
	v_and_b32_e32 v4, -16, v4
	v_sub_u32_e32 v4, v40, v4
	v_mul_lo_u32 v7, v6, s4
	v_lshl_add_u32 v34, v4, 4, v7
	v_lshlrev_b32_e32 v7, 8, v6
	v_bitop3_b32 v4, v6, v4, 7 bitop3:0x6c
	v_lshl_add_u32 v20, v4, 4, v7
	v_add_u32_e32 v4, 0x200, v40
	v_ashrrev_i32_e32 v6, 31, v4
	v_lshrrev_b32_e32 v6, 28, v6
	v_add_u32_e32 v6, v4, v6
	v_ashrrev_i32_e32 v7, 4, v6
	v_and_b32_e32 v6, -16, v6
	v_sub_u32_e32 v4, v4, v6
	v_mul_lo_u32 v6, v7, s4
	s_mul_hi_u32 s5, s20, s26
	s_mul_i32 s4, s20, s26
	s_lshl_b64 s[4:5], s[4:5], 7
	s_add_u32 s18, s8, s4
	v_lshlrev_b32_e32 v147, 4, v40
	s_addc_u32 s19, s9, s5
	v_lshlrev_b32_e32 v5, 9, v5
	v_lshl_add_u32 v36, v4, 4, v6
	v_lshlrev_b32_e32 v6, 8, v7
	v_bitop3_b32 v4, v7, v4, 7 bitop3:0x6c
	v_and_b32_e32 v22, 48, v147
	v_lshlrev_b32_e32 v166, 1, v3
	s_add_u32 s4, s6, s4
	v_lshl_add_u32 v21, v4, 4, v6
	v_or3_b32 v23, v5, v18, v22
	v_lshlrev_b32_e32 v38, 1, v2
	s_addc_u32 s5, s7, s5
	global_load_dwordx4 v[2:5], v166, s[18:19]
	global_load_dwordx4 v[6:9], v38, s[18:19]
	global_load_dwordx4 v[10:13], v34, s[4:5]
	global_load_dwordx4 v[14:17], v36, s[4:5]
	s_add_i32 s100, s20, 1
	s_mul_hi_u32 s101, s100, s26
	s_mul_i32 s100, s100, s26
	s_lshl_b64 s[100:101], s[100:101], 7
	s_add_u32 s100, s8, s100
	s_addc_u32 s101, s9, s101
	global_load_dwordx4 v[66:69], v166, s[100:101]
	global_load_dwordx4 v[70:73], v38, s[100:101]
	s_sub_u32 s100, s100, s8
	s_subb_u32 s101, s101, s9
	s_add_u32 s100, s100, s6
	s_addc_u32 s101, s101, s7
	global_load_dwordx4 v[74:77], v34, s[100:101]
	global_load_dwordx4 v[78:81], v36, s[100:101]
	v_add_u32_e32 v208, 0, v23
	s_movk_i32 s4, 0x70
	v_or3_b32 v18, v19, v18, v22
	v_lshl_add_u32 v37, v165, 8, 0
	v_add_u32_e32 v209, 0, v18
	v_add_u32_e32 v210, 0, v20
	v_add_u32_e32 v211, 0, v21
	v_and_b32_e32 v35, 0x70, v147
	v_bitop3_b32 v39, v146, v35, 32 bitop3:0x36
	v_add_u32_e32 v186, v37, v39
	v_bitop3_b32 v39, v146, v35, 64 bitop3:0x36
	v_add_u32_e32 v187, v37, v39
	s_cmp_lt_u32 s84, s80
	s_cselect_b64 s[18:19], -1, 0
	s_cmp_ge_u32 s84, s80
	s_waitcnt vmcnt(7)
	ds_write_b128 v208, v[2:5]
	v_bitop3_b32 v2, v146, v147, s4 bitop3:0x78
	v_add_u32_e32 v185, v37, v2
	s_waitcnt vmcnt(6)
	ds_write_b128 v209, v[6:9]
	s_waitcnt vmcnt(5)
	ds_write_b128 v210, v[10:13] offset:32768
	s_waitcnt vmcnt(4)
	ds_write_b128 v211, v[14:17] offset:32768
	s_waitcnt lgkmcnt(0)
	s_barrier
	ds_read_b128 v[2:5], v185 offset:32768
	ds_read_b128 v[6:9], v185 offset:40960
	s_waitcnt lgkmcnt(1)
	v_mfma_f32_32x32x16_bf16 v[18:33], v[2:5], v[142:145], 0
	ds_read_b128 v[42:45], v186 offset:32768
	ds_read_b128 v[46:49], v186 offset:40960
	s_movk_i32 s4, 0x60
	v_bitop3_b32 v39, v146, v35, s4 bitop3:0x36
	v_add_u32_e32 v188, v37, v39
	s_movk_i32 s4, 0x80
	v_bitop3_b32 v39, v146, v35, s4 bitop3:0x36
	v_add_u32_e32 v189, v37, v39
	s_waitcnt lgkmcnt(2)
	v_mfma_f32_32x32x16_bf16 v[2:17], v[6:9], v[142:145], 0
	s_movk_i32 s4, 0xa0
	v_bitop3_b32 v39, v146, v35, s4 bitop3:0x36
	v_add_u32_e32 v205, v37, v39
	s_movk_i32 s4, 0xc0
	v_bitop3_b32 v39, v146, v35, s4 bitop3:0x36
	v_add_u32_e32 v206, v37, v39
	s_movk_i32 s4, 0xe0
	s_waitcnt lgkmcnt(1)
	v_mfma_f32_32x32x16_bf16 v[18:33], v[42:45], v[138:141], v[18:33]
	v_bitop3_b32 v35, v146, v35, s4 bitop3:0x36
	v_add_u32_e32 v207, v37, v35
	s_waitcnt lgkmcnt(0)
	v_mfma_f32_32x32x16_bf16 v[2:17], v[46:49], v[138:141], v[2:17]
	ds_read_b128 v[42:45], v187 offset:32768
	ds_read_b128 v[46:49], v187 offset:40960
	s_waitcnt lgkmcnt(1)
	v_mfma_f32_32x32x16_bf16 v[18:33], v[42:45], v[134:137], v[18:33]
	s_waitcnt lgkmcnt(0)
	v_mfma_f32_32x32x16_bf16 v[2:17], v[46:49], v[134:137], v[2:17]
	ds_read_b128 v[42:45], v188 offset:32768
	ds_read_b128 v[46:49], v188 offset:40960
	s_waitcnt lgkmcnt(1)
	v_mfma_f32_32x32x16_bf16 v[18:33], v[42:45], v[130:133], v[18:33]
	s_waitcnt lgkmcnt(0)
	v_mfma_f32_32x32x16_bf16 v[2:17], v[46:49], v[130:133], v[2:17]
	ds_read_b128 v[42:45], v189 offset:32768
	ds_read_b128 v[46:49], v189 offset:40960
	s_waitcnt lgkmcnt(1)
	v_mfma_f32_32x32x16_bf16 v[18:33], v[42:45], v[126:129], v[18:33]
	s_waitcnt lgkmcnt(0)
	v_mfma_f32_32x32x16_bf16 v[2:17], v[46:49], v[126:129], v[2:17]
	ds_read_b128 v[42:45], v205 offset:32768
	ds_read_b128 v[46:49], v205 offset:40960
	s_waitcnt lgkmcnt(1)
	v_mfma_f32_32x32x16_bf16 v[18:33], v[42:45], v[122:125], v[18:33]
	s_waitcnt lgkmcnt(0)
	v_mfma_f32_32x32x16_bf16 v[2:17], v[46:49], v[122:125], v[2:17]
	ds_read_b128 v[42:45], v206 offset:32768
	ds_read_b128 v[46:49], v206 offset:40960
	s_waitcnt lgkmcnt(1)
	v_mfma_f32_32x32x16_bf16 v[18:33], v[42:45], v[118:121], v[18:33]
	s_waitcnt lgkmcnt(0)
	v_mfma_f32_32x32x16_bf16 v[2:17], v[46:49], v[118:121], v[2:17]
	ds_read_b128 v[42:45], v207 offset:32768
	ds_read_b128 v[46:49], v207 offset:40960
	s_waitcnt lgkmcnt(1)
	v_mfma_f32_32x32x16_bf16 v[18:33], v[42:45], v[114:117], v[18:33]
	s_waitcnt lgkmcnt(0)
	v_mfma_f32_32x32x16_bf16 v[2:17], v[46:49], v[114:117], v[2:17]
	s_cbranch_scc1 .LBB0_588
	s_lshl_b32 s4, s20, 6
	v_lshl_or_b32 v35, v164, 2, s4
	s_sub_i32 s21, 0, s84
	v_sub_u32_e32 v37, v179, v35
	v_cmp_lt_i32_e32 vcc, s84, v37
	v_cmp_gt_i32_e64 s[4:5], s21, v37
	s_or_b64 vcc, vcc, s[4:5]
	v_subrev_u32_e32 v37, 32, v37
	s_nop 0
	v_cndmask_b32_e32 v18, v18, v203, vcc
	v_cmp_lt_i32_e32 vcc, s84, v37
	v_cmp_gt_i32_e64 s[4:5], s21, v37
	s_or_b64 vcc, vcc, s[4:5]
	v_xad_u32 v37, v35, -1, v179
	v_cndmask_b32_e32 v2, v2, v203, vcc
	v_cmp_lt_i32_e32 vcc, s84, v37
	v_cmp_gt_i32_e64 s[4:5], s21, v37
	s_or_b64 vcc, vcc, s[4:5]
	v_subrev_u32_e32 v37, 32, v37
	v_cndmask_b32_e32 v19, v19, v203, vcc
	v_cmp_lt_i32_e32 vcc, s84, v37
	v_cmp_gt_i32_e64 s[4:5], s21, v37
	v_or_b32_e32 v37, 2, v35
	s_or_b64 vcc, vcc, s[4:5]
	v_sub_u32_e32 v37, v179, v37
	v_cndmask_b32_e32 v3, v3, v203, vcc
	v_cmp_lt_i32_e32 vcc, s84, v37
	v_cmp_gt_i32_e64 s[4:5], s21, v37
	s_or_b64 vcc, vcc, s[4:5]
	v_subrev_u32_e32 v37, 32, v37
	v_cndmask_b32_e32 v20, v20, v203, vcc
	v_cmp_lt_i32_e32 vcc, s84, v37
	v_cmp_gt_i32_e64 s[4:5], s21, v37
	v_or_b32_e32 v37, 3, v35
	s_or_b64 vcc, vcc, s[4:5]
	v_sub_u32_e32 v37, v179, v37
	v_cndmask_b32_e32 v4, v4, v203, vcc
	v_cmp_lt_i32_e32 vcc, s84, v37
	v_cmp_gt_i32_e64 s[4:5], s21, v37
	s_or_b64 vcc, vcc, s[4:5]
	v_subrev_u32_e32 v37, 32, v37
	v_cndmask_b32_e32 v21, v21, v203, vcc
	v_cmp_lt_i32_e32 vcc, s84, v37
	v_cmp_gt_i32_e64 s[4:5], s21, v37
	v_or_b32_e32 v37, 8, v35
	s_or_b64 vcc, vcc, s[4:5]
	v_sub_u32_e32 v37, v179, v37
	v_cndmask_b32_e32 v5, v5, v203, vcc
	v_cmp_lt_i32_e32 vcc, s84, v37
	v_cmp_gt_i32_e64 s[4:5], s21, v37
	s_or_b64 vcc, vcc, s[4:5]
	v_subrev_u32_e32 v37, 32, v37
	v_cndmask_b32_e32 v22, v22, v203, vcc
	v_cmp_lt_i32_e32 vcc, s84, v37
	v_cmp_gt_i32_e64 s[4:5], s21, v37
	v_or_b32_e32 v37, 9, v35
	s_or_b64 vcc, vcc, s[4:5]
	v_sub_u32_e32 v37, v179, v37
	v_cndmask_b32_e32 v6, v6, v203, vcc
	v_cmp_lt_i32_e32 vcc, s84, v37
	v_cmp_gt_i32_e64 s[4:5], s21, v37
	s_or_b64 vcc, vcc, s[4:5]
	v_subrev_u32_e32 v37, 32, v37
	v_cndmask_b32_e32 v23, v23, v203, vcc
	v_cmp_lt_i32_e32 vcc, s84, v37
	v_cmp_gt_i32_e64 s[4:5], s21, v37
	v_or_b32_e32 v37, 10, v35
	s_or_b64 vcc, vcc, s[4:5]
	v_sub_u32_e32 v37, v179, v37
	v_cndmask_b32_e32 v7, v7, v203, vcc
	v_cmp_lt_i32_e32 vcc, s84, v37
	v_cmp_gt_i32_e64 s[4:5], s21, v37
	s_or_b64 vcc, vcc, s[4:5]
	v_subrev_u32_e32 v37, 32, v37
	v_cndmask_b32_e32 v24, v24, v203, vcc
	v_cmp_lt_i32_e32 vcc, s84, v37
	v_cmp_gt_i32_e64 s[4:5], s21, v37
	v_or_b32_e32 v37, 11, v35
	s_or_b64 vcc, vcc, s[4:5]
	v_sub_u32_e32 v37, v179, v37
	v_cndmask_b32_e32 v8, v8, v203, vcc
	v_cmp_lt_i32_e32 vcc, s84, v37
	v_cmp_gt_i32_e64 s[4:5], s21, v37
	s_or_b64 vcc, vcc, s[4:5]
	v_subrev_u32_e32 v37, 32, v37
	v_cndmask_b32_e32 v25, v25, v203, vcc
	v_cmp_lt_i32_e32 vcc, s84, v37
	v_cmp_gt_i32_e64 s[4:5], s21, v37
	v_or_b32_e32 v37, 16, v35
	s_or_b64 vcc, vcc, s[4:5]
	v_sub_u32_e32 v37, v179, v37
	v_cndmask_b32_e32 v9, v9, v203, vcc
	v_cmp_lt_i32_e32 vcc, s84, v37
	v_cmp_gt_i32_e64 s[4:5], s21, v37
	s_or_b64 vcc, vcc, s[4:5]
	v_subrev_u32_e32 v37, 32, v37
	v_cndmask_b32_e32 v26, v26, v203, vcc
	v_cmp_lt_i32_e32 vcc, s84, v37
	v_cmp_gt_i32_e64 s[4:5], s21, v37
	v_or_b32_e32 v37, 17, v35
	s_or_b64 vcc, vcc, s[4:5]
	v_sub_u32_e32 v37, v179, v37
	v_cndmask_b32_e32 v10, v10, v203, vcc
	v_cmp_lt_i32_e32 vcc, s84, v37
	v_cmp_gt_i32_e64 s[4:5], s21, v37
	s_or_b64 vcc, vcc, s[4:5]
	v_subrev_u32_e32 v37, 32, v37
	v_cndmask_b32_e32 v27, v27, v203, vcc
	v_cmp_lt_i32_e32 vcc, s84, v37
	v_cmp_gt_i32_e64 s[4:5], s21, v37
	v_or_b32_e32 v37, 18, v35
	s_or_b64 vcc, vcc, s[4:5]
	v_sub_u32_e32 v37, v179, v37
	v_cndmask_b32_e32 v11, v11, v203, vcc
	v_cmp_lt_i32_e32 vcc, s84, v37
	v_cmp_gt_i32_e64 s[4:5], s21, v37
	s_or_b64 vcc, vcc, s[4:5]
	v_subrev_u32_e32 v37, 32, v37
	v_cndmask_b32_e32 v28, v28, v203, vcc
	v_cmp_lt_i32_e32 vcc, s84, v37
	v_cmp_gt_i32_e64 s[4:5], s21, v37
	v_or_b32_e32 v37, 19, v35
	s_or_b64 vcc, vcc, s[4:5]
	v_sub_u32_e32 v37, v179, v37
	v_cndmask_b32_e32 v12, v12, v203, vcc
	v_cmp_lt_i32_e32 vcc, s84, v37
	v_cmp_gt_i32_e64 s[4:5], s21, v37
	s_or_b64 vcc, vcc, s[4:5]
	v_subrev_u32_e32 v37, 32, v37
	v_cndmask_b32_e32 v29, v29, v203, vcc
	v_cmp_lt_i32_e32 vcc, s84, v37
	v_cmp_gt_i32_e64 s[4:5], s21, v37
	v_or_b32_e32 v37, 24, v35
	s_or_b64 vcc, vcc, s[4:5]
	v_sub_u32_e32 v37, v179, v37
	v_cndmask_b32_e32 v13, v13, v203, vcc
	v_cmp_lt_i32_e32 vcc, s84, v37
	v_cmp_gt_i32_e64 s[4:5], s21, v37
	s_or_b64 vcc, vcc, s[4:5]
	v_subrev_u32_e32 v37, 32, v37
	v_cndmask_b32_e32 v30, v30, v203, vcc
	v_cmp_lt_i32_e32 vcc, s84, v37
	v_cmp_gt_i32_e64 s[4:5], s21, v37
	v_or_b32_e32 v37, 25, v35
	s_or_b64 vcc, vcc, s[4:5]
	v_sub_u32_e32 v37, v179, v37
	v_cndmask_b32_e32 v14, v14, v203, vcc
	v_cmp_lt_i32_e32 vcc, s84, v37
	v_cmp_gt_i32_e64 s[4:5], s21, v37
	s_or_b64 vcc, vcc, s[4:5]
	v_subrev_u32_e32 v37, 32, v37
	v_cndmask_b32_e32 v31, v31, v203, vcc
	v_cmp_lt_i32_e32 vcc, s84, v37
	v_cmp_gt_i32_e64 s[4:5], s21, v37
	v_or_b32_e32 v37, 26, v35
	s_or_b64 vcc, vcc, s[4:5]
	v_sub_u32_e32 v37, v179, v37
	v_cndmask_b32_e32 v15, v15, v203, vcc
	v_cmp_lt_i32_e32 vcc, s84, v37
	v_cmp_gt_i32_e64 s[4:5], s21, v37
	s_or_b64 vcc, vcc, s[4:5]
	v_subrev_u32_e32 v37, 32, v37
	v_cndmask_b32_e32 v32, v32, v203, vcc
	v_cmp_lt_i32_e32 vcc, s84, v37
	v_cmp_gt_i32_e64 s[4:5], s21, v37
	v_or_b32_e32 v35, 27, v35
	s_or_b64 vcc, vcc, s[4:5]
	v_sub_u32_e32 v35, v179, v35
	v_cndmask_b32_e32 v16, v16, v203, vcc
	v_cmp_lt_i32_e32 vcc, s84, v35
	v_cmp_gt_i32_e64 s[4:5], s21, v35
	s_or_b64 vcc, vcc, s[4:5]
	v_subrev_u32_e32 v35, 32, v35
	v_cndmask_b32_e32 v33, v33, v203, vcc
	v_cmp_lt_i32_e32 vcc, s84, v35
	v_cmp_gt_i32_e64 s[4:5], s21, v35
	s_or_b64 vcc, vcc, s[4:5]
	v_cndmask_b32_e32 v17, v17, v203, vcc
.LBB0_588:
	v_and_b32_e32 v180, 63, v40
	v_and_b32_e32 v40, 0x3fffffc0, v40
	s_add_i32 s4, 0, 0x10000
	v_lshlrev_b32_e32 v41, 4, v180
	v_lshl_add_u32 v181, v40, 2, s4
	v_lshlrev_b32_e32 v40, 3, v180
	v_and_b32_e32 v41, 0xc0, v41
	v_lshlrev_b32_e32 v42, 1, v180
	v_and_or_b32 v41, v40, 24, v41
	v_and_b32_e32 v42, 32, v42
	v_and_b32_e32 v40, 0x100, v40
	v_or3_b32 v182, v41, v42, v40
	v_max_f32_e32 v40, v19, v19
	v_max_f32_e32 v41, v18, v18
	v_max_f32_e32 v40, v41, v40
	v_max3_f32 v40, v40, v20, v21
	v_max3_f32 v40, v40, v22, v23
	v_max3_f32 v40, v40, v24, v25
	v_max3_f32 v40, v40, v26, v27
	v_max3_f32 v40, v40, v28, v29
	v_max3_f32 v40, v40, v30, v31
	v_max3_f32 v40, v40, v32, v33
	v_max3_f32 v40, v40, v2, v3
	v_max3_f32 v40, v40, v4, v5
	v_max3_f32 v40, v40, v6, v7
	v_max3_f32 v40, v40, v8, v9
	v_max3_f32 v40, v40, v10, v11
	v_max3_f32 v40, v40, v12, v13
	v_max3_f32 v40, v40, v14, v15
	v_max3_f32 v40, v40, v16, v17
	v_mov_b32_e32 v41, v40
	s_nop 1
	v_permlane32_swap_b32_e32 v40, v41
	v_max_f32_e32 v41, v41, v41
	v_max_f32_e32 v40, v40, v40
	v_max_f32_e32 v40, v40, v41
	s_cmp_lg_u32 0, -1
	v_add_f32_e32 v41, 0x7149f2ca, v40
	s_cselect_b32 s4, 0, 0
	s_sub_i32 s87, s85, s20
	v_cmp_ge_f32_e32 vcc, s40, v41
	s_cmp_eq_u64 vcc, exec
	v_add_u32_e32 v184, s4, v182
	s_cselect_b64 vcc, -1, 0
	s_add_i32 s4, s20, 1
	v_max_f32_e32 v40, 0xf149f2ca, v40
	s_mul_hi_u32 s5, s4, s26
	s_mul_i32 s4, s4, s26
	v_cndmask_b32_e32 v212, v40, v203, vcc
	s_lshl_b64 s[4:5], s[4:5], 7
	v_sub_f32_e32 v41, 0xf149f2ca, v40
	v_mul_f32_e32 v40, 0xbe0293ee, v212
	s_add_u32 s22, s8, s4
	v_fmamk_f32 v18, v18, 0x3e0293ee, v40
	v_fmamk_f32 v19, v19, 0x3e0293ee, v40
	s_addc_u32 s23, s9, s5
	v_mov_b32_e32 v39, v167
	v_fmamk_f32 v20, v20, 0x3e0293ee, v40
	v_fmamk_f32 v21, v21, 0x3e0293ee, v40
	v_fmamk_f32 v22, v22, 0x3e0293ee, v40
	v_fmamk_f32 v23, v23, 0x3e0293ee, v40
	v_exp_f32_e32 v223, v18
	v_exp_f32_e32 v225, v19
	s_add_u32 s4, s6, s4
	v_lshl_add_u64 v[18:19], s[22:23], 0, v[166:167]
	v_mov_b32_e32 v35, v167
	v_fmamk_f32 v24, v24, 0x3e0293ee, v40
	v_fmamk_f32 v25, v25, 0x3e0293ee, v40
	v_fmamk_f32 v26, v26, 0x3e0293ee, v40
	v_fmamk_f32 v27, v27, 0x3e0293ee, v40
	v_exp_f32_e32 v226, v20
	v_exp_f32_e32 v227, v21
	v_exp_f32_e32 v228, v22
	v_exp_f32_e32 v229, v23
	s_addc_u32 s5, s7, s5
	v_lshl_add_u64 v[22:23], s[22:23], 0, v[38:39]
	v_mov_b32_e32 v37, v167
	v_fmamk_f32 v28, v28, 0x3e0293ee, v40
	v_fmamk_f32 v29, v29, 0x3e0293ee, v40
	v_fmamk_f32 v30, v30, 0x3e0293ee, v40
	v_fmamk_f32 v31, v31, 0x3e0293ee, v40
	v_exp_f32_e32 v230, v24
	v_exp_f32_e32 v231, v25
	v_exp_f32_e32 v216, v26
	v_exp_f32_e32 v217, v27
	v_lshl_add_u64 v[26:27], s[4:5], 0, v[34:35]
	v_fmamk_f32 v32, v32, 0x3e0293ee, v40
	v_fmamk_f32 v33, v33, 0x3e0293ee, v40
	v_exp_f32_e32 v218, v28
	v_exp_f32_e32 v219, v29
	v_exp_f32_e32 v220, v30
	v_exp_f32_e32 v221, v31
	v_lshl_add_u64 v[30:31], s[4:5], 0, v[36:37]
	v_exp_f32_e32 v222, v32
	v_exp_f32_e32 v224, v33
	v_mul_f32_e32 v41, 0x3e0293ee, v41
	v_exp_f32_e32 v41, v41
	s_cmp_lt_i32 s87, 3
	v_cmp_gt_u32_e64 s[4:5], 32, v180
	v_lshl_add_u32 v183, v165, 2, v181
	v_cndmask_b32_e64 v213, v41, 1.0, vcc
	v_pk_fma_f32 v[98:99], v[16:17], s[54:55], v[40:41] op_sel_hi:[1,0,0]
	v_pk_fma_f32 v[100:101], v[14:15], s[54:55], v[40:41] op_sel_hi:[1,0,0]
	v_pk_fma_f32 v[102:103], v[12:13], s[54:55], v[40:41] op_sel_hi:[1,0,0]
	v_pk_fma_f32 v[104:105], v[10:11], s[54:55], v[40:41] op_sel_hi:[1,0,0]
	v_pk_fma_f32 v[106:107], v[8:9], s[54:55], v[40:41] op_sel_hi:[1,0,0]
	v_pk_fma_f32 v[108:109], v[6:7], s[54:55], v[40:41] op_sel_hi:[1,0,0]
	v_pk_fma_f32 v[110:111], v[4:5], s[54:55], v[40:41] op_sel_hi:[1,0,0]
	v_pk_fma_f32 v[112:113], v[2:3], s[54:55], v[40:41] op_sel_hi:[1,0,0]
	v_mov_b32_e32 v17, 0
	s_waitcnt vmcnt(3)
	ds_write_b128 v208, v[66:69] offset:16384
	s_waitcnt vmcnt(2)
	ds_write_b128 v209, v[70:73] offset:16384
	s_waitcnt vmcnt(1)
	ds_write_b128 v210, v[74:77] offset:49152
	s_waitcnt vmcnt(0)
	ds_write_b128 v211, v[78:81] offset:49152
	s_waitcnt lgkmcnt(0)
	s_barrier
	s_cbranch_scc1 .LBB0_604
	s_cmp_lg_u32 0, -1
	s_cselect_b32 s21, 0, 0
	s_addk_i32 s21, 0x4000
	v_add_u32_e32 v214, s21, v182
	s_add_i32 s21, s82, 0xffffffa5
	v_lshlrev_b32_e32 v2, 2, v164
	v_add3_u32 v3, s21, v1, v165
	v_sub_u32_e32 v2, v3, v2
	s_lshl_b32 s21, s20, 6
	v_subrev_u32_e32 v215, s21, v2
	s_ashr_i32 s21, s20, 31
	s_add_i32 s87, s87, -3
	s_sub_i32 s88, 0, s84
	s_lshl_b64 s[22:23], s[20:21], 7
	s_add_u32 s20, s22, 0x180
	s_addc_u32 s21, s23, 0
	s_mul_i32 s21, s21, s26
	s_mul_hi_u32 s46, s20, s26
	s_add_i32 s48, s46, s21
	s_mul_i32 s49, s20, s26
	s_add_u32 s46, s8, s49
	s_addc_u32 s47, s9, s48
	s_lshl_b64 s[20:21], s[26:27], 8
	v_lshl_add_u64 v[148:149], s[46:47], 0, v[166:167]
	v_lshl_add_u64 v[150:151], s[46:47], 0, v[38:39]
	s_add_u32 s46, s6, s49
	s_addc_u32 s47, s7, s48
	s_add_u32 s22, s22, 0x100
	s_addc_u32 s23, s23, 0
	v_lshl_add_u64 v[152:153], s[46:47], 0, v[34:35]
	v_lshl_add_u64 v[154:155], s[46:47], 0, v[36:37]
	s_mul_i32 s23, s23, s26
	s_mul_hi_u32 s46, s22, s26
	s_add_i32 s46, s46, s23
	s_mul_i32 s22, s22, s26
	s_add_u32 s8, s8, s22
	s_addc_u32 s9, s9, s46
	s_add_u32 s6, s6, s22
	v_lshl_add_u64 v[156:157], s[8:9], 0, v[166:167]
	s_addc_u32 s7, s7, s46
	v_mov_b32_e32 v166, 0
	s_mov_b32 s86, -1
	v_lshl_add_u64 v[158:159], s[8:9], 0, v[38:39]
	v_lshl_add_u64 v[160:161], s[6:7], 0, v[34:35]
	v_lshl_add_u64 v[162:163], s[6:7], 0, v[36:37]
	s_mov_b64 s[22:23], 0
	v_mov_b32_e32 v50, 0
	v_mov_b32_e32 v51, v166
	v_mov_b32_e32 v52, v166
	v_mov_b32_e32 v53, v166
	v_mov_b32_e32 v54, v166
	v_mov_b32_e32 v55, v166
	v_mov_b32_e32 v56, v166
	v_mov_b32_e32 v57, v166
	v_mov_b32_e32 v58, v166
	v_mov_b32_e32 v59, v166
	v_mov_b32_e32 v60, v166
	v_mov_b32_e32 v61, v166
	v_mov_b32_e32 v62, v166
	v_mov_b32_e32 v63, v166
	v_mov_b32_e32 v64, v166
	v_mov_b32_e32 v65, v166
	v_mov_b32_e32 v34, 0
	v_mov_b32_e32 v35, v166
	v_mov_b32_e32 v36, v166
	v_mov_b32_e32 v37, v166
	v_mov_b32_e32 v38, v166
	v_mov_b32_e32 v39, v166
	v_mov_b32_e32 v40, v166
	v_mov_b32_e32 v41, v166
	v_mov_b32_e32 v42, v166
	v_mov_b32_e32 v43, v166
	v_mov_b32_e32 v44, v166
	v_mov_b32_e32 v45, v166
	v_mov_b32_e32 v46, v166
	v_mov_b32_e32 v47, v166
	v_mov_b32_e32 v48, v166
	v_mov_b32_e32 v49, v166
	v_mov_b32_e32 v18, 0
	v_mov_b32_e32 v19, v166
	v_mov_b32_e32 v20, v166
	v_mov_b32_e32 v21, v166
	v_mov_b32_e32 v22, v166
	v_mov_b32_e32 v23, v166
	v_mov_b32_e32 v24, v166
	v_mov_b32_e32 v25, v166
	v_mov_b32_e32 v26, v166
	v_mov_b32_e32 v27, v166
	v_mov_b32_e32 v28, v166
	v_mov_b32_e32 v29, v166
	v_mov_b32_e32 v30, v166
	v_mov_b32_e32 v31, v166
	v_mov_b32_e32 v32, v166
	v_mov_b32_e32 v33, v166
	v_mov_b32_e32 v2, 0
	v_mov_b32_e32 v3, v166
	v_mov_b32_e32 v4, v166
	v_mov_b32_e32 v5, v166
	v_mov_b32_e32 v6, v166
	v_mov_b32_e32 v7, v166
	v_mov_b32_e32 v8, v166
	v_mov_b32_e32 v9, v166
	v_mov_b32_e32 v10, v166
	v_mov_b32_e32 v11, v166
	v_mov_b32_e32 v12, v166
	v_mov_b32_e32 v13, v166
	v_mov_b32_e32 v14, v166
	v_mov_b32_e32 v15, v166
	v_mov_b32_e32 v16, v166
	v_mov_b32_e32 v17, v166
	s_movk_i32 s26, 0x110
